# stack: v13 + P4a DPP reductions + attention epilogue dwordx4 stores + all s_setprio toggles deleted
# speedup vs baseline: 1.0122x; 1.0084x over previous
; __device__ __forceinline__ unsigned pk2(float a, float b) { f32x2_t v = {a, b}; bf16x2v_t r = __builtin_convertvector(v, bf16x2v_t); return __builtin_bit_cast(unsigned, r); }
; #define LAS __attribute__((address_space(3)))
; __device__ __forceinline__ void attn_unit(LAS unsigned char* lds, const bf16_t* Qg, const bf16_t* Kg, const bf16_t* Vtg, bf16_t* Og, int bh, int qb, int tid_, int wave, int lane_) {
;     ...
;     asm volatile("s_waitcnt vmcnt(0) lgkmcnt(0)" ::: "memory"); __builtin_amdgcn_s_barrier(); asm volatile("" ::: "memory");
;     LAS float* cs = (LAS float*)(lds + rg * (66 * 64 * 4)) + lane;
;     if (kh == 1) {
; #pragma unroll
;         for (int dt = 0; dt < 4; ++dt)
; #pragma unroll
;             for (int i = 0; i < 16; ++i) cs[(dt * 16 + i) * 64] = o[dt][i];
;         cs[64 * 64] = mrun; cs[65 * 64] = lrun;
;     }
;     __syncthreads();
;     if (kh == 0) {
;         const float m1 = cs[64 * 64], l1 = cs[65 * 64];
;         const float mf = fmaxf(mrun, m1), a0 = __builtin_amdgcn_exp2f(mrun - mf), a1 = __builtin_amdgcn_exp2f(m1 - mf);
;         float lt = lrun * a0 + l1 * a1; lt += __shfl_xor(lt, 32);
;         const float inv = 1.f / lt;
;         bf16_t* op = Og + ((size_t)b * SEQ + 128 * qb + 32 * rg + r) * AW + h * VD + 4 * hi;
; #pragma unroll
;         for (int dt = 0; dt < 4; ++dt)
; #pragma unroll
;             for (int g = 0; g < 4; ++g) {
;                 float v[4];
; #pragma unroll
;                 for (int e = 0; e < 4; ++e) v[e] = (o[dt][4 * g + e] * a0 + cs[(dt * 16 + 4 * g + e) * 64] * a1) * inv;
;                 u32x2 w; w.x = pk2(v[0], v[1]); w.y = pk2(v[2], v[3]);
;                 *(u32x2*)(op + 32 * dt + 8 * g) = w;
;             }
;     }
.LBB0_484:
	v_cndmask_b32_e64 v64, 0, 1, s[76:77]
	v_cmp_ne_u32_e64 s[6:7], 1, v64
	v_mbcnt_lo_u32_b32 v64, -1, 0
	s_andn2_b64 vcc, exec, s[76:77]
	v_mbcnt_hi_u32_b32 v197, -1, v64
	s_waitcnt vmcnt(0) lgkmcnt(0)
	s_barrier
	s_cbranch_vccnz .LBB0_486
	ds_read2st64_b32 v[64:65], v67 offset0:64 offset1:65
	ds_read2st64_b32 v[72:73], v67 offset1:1
	v_max_f32_e32 v66, v204, v204
	v_xor_b32_e32 v70, 32, v197
	ds_read2st64_b32 v[74:75], v67 offset0:2 offset1:3
	ds_read2st64_b32 v[76:77], v67 offset0:4 offset1:5
	ds_read2st64_b32 v[78:79], v67 offset0:6 offset1:7
	s_waitcnt lgkmcnt(4)
	v_max_f32_e32 v68, v64, v64
	v_max_f32_e32 v66, v66, v68
	v_sub_f32_e32 v68, v204, v66
	v_sub_f32_e32 v66, v64, v66
	v_exp_f32_e32 v64, v68
	v_exp_f32_e32 v191, v66
	v_and_b32_e32 v66, 64, v197
	v_add_u32_e32 v66, 64, v66
	v_cmp_lt_i32_e32 vcc, v70, v66
	v_pk_mul_f32 v[68:69], v[190:191], v[64:65]
	v_lshlrev_b32_e32 v176, 1, v198
	v_cndmask_b32_e32 v66, v197, v70, vcc
	v_add_f32_e32 v65, v68, v69
	v_lshlrev_b32_e32 v66, 2, v66
	ds_bpermute_b32 v66, v66, v65
	s_waitcnt lgkmcnt(0)
	v_add_f32_e32 v65, v65, v66
	v_div_scale_f32 v66, s[0:1], v65, v65, 1.0
	v_rcp_f32_e32 v68, v66
	v_div_scale_f32 v69, vcc, 1.0, v65, 1.0
	s_lshl_b32 s0, s73, 11
	v_fma_f32 v70, -v66, v68, 1.0
	v_fmac_f32_e32 v68, v70, v68
	v_mul_f32_e32 v70, v69, v68
	v_fma_f32 v71, -v66, v70, v69
	v_fmac_f32_e32 v70, v71, v68
	v_fma_f32 v66, -v66, v70, v69
	s_and_b32 s0, s0, 0x2000
	v_div_fmas_f32 v66, v66, v68, v70
	s_add_u32 s0, s0, s66
	v_div_fixup_f32 v66, v66, v65, 1.0
	s_addc_u32 s1, 0, s88
	v_mov_b32_e32 v65, s97
	v_or3_b32 v69, s1, 0, 0
	v_or3_b32 v68, s0, v65, v180
	v_readlane_b32 s0, v255, 34
	v_mov_b32_e32 v70, v191
	v_lshlrev_b64 v[68:69], 10, v[68:69]
	v_readlane_b32 s1, v255, 35
	v_pk_mul_f32 v[72:73], v[70:71], v[72:73] op_sel_hi:[0,1]
	v_pk_fma_f32 v[48:49], v[48:49], v[64:65], v[72:73] op_sel_hi:[1,0,1]
	v_lshl_add_u64 v[68:69], s[0:1], 0, v[68:69]
	s_lshl_b32 s0, s73, 8
	v_pk_mul_f32 v[72:73], v[70:71], v[74:75] op_sel_hi:[0,1]
	s_and_b32 s48, s0, 0x300
	v_pk_fma_f32 v[50:51], v[50:51], v[64:65], v[72:73] op_sel_hi:[1,0,1]
	v_lshl_add_u64 v[68:69], v[68:69], 0, s[48:49]
	v_pk_mul_f32 v[48:49], v[48:49], v[66:67] op_sel_hi:[1,0]
	v_pk_mul_f32 v[50:51], v[66:67], v[50:51] op_sel_hi:[0,1]
	v_lshl_add_u64 v[68:69], v[68:69], 0, v[176:177]
	v_lshl_add_u64 v[112:113], v[68:69], 0, v[176:177]
	v_cvt_pk_bf16_f32 v96, v48, v49
	v_cvt_pk_bf16_f32 v97, v50, v51
	v_pk_mul_f32 v[48:49], v[70:71], v[76:77] op_sel_hi:[0,1]
	v_pk_mul_f32 v[50:51], v[70:71], v[78:79] op_sel_hi:[0,1]
	v_pk_fma_f32 v[48:49], v[52:53], v[64:65], v[48:49] op_sel_hi:[1,0,1]
	v_pk_fma_f32 v[50:51], v[54:55], v[64:65], v[50:51] op_sel_hi:[1,0,1]
	v_pk_mul_f32 v[48:49], v[66:67], v[48:49] op_sel_hi:[0,1]
	v_pk_mul_f32 v[50:51], v[66:67], v[50:51] op_sel_hi:[0,1]
	v_cvt_pk_bf16_f32 v98, v48, v49
	v_cvt_pk_bf16_f32 v99, v50, v51
	ds_read2st64_b32 v[50:51], v67 offset0:8 offset1:9
	s_nop 1
	v_permlane32_swap_b32_e32 v96, v98
	v_permlane32_swap_b32_e32 v97, v99
	global_store_dwordx4 v[112:113], v[96:99], off
	ds_read2st64_b32 v[48:49], v67 offset0:10 offset1:11
	ds_read2st64_b32 v[52:53], v67 offset0:12 offset1:13
	ds_read2st64_b32 v[54:55], v67 offset0:14 offset1:15
	s_waitcnt lgkmcnt(3)
	v_pk_mul_f32 v[50:51], v[70:71], v[50:51] op_sel_hi:[0,1]
	s_waitcnt lgkmcnt(2)
	v_pk_mul_f32 v[48:49], v[70:71], v[48:49] op_sel_hi:[0,1]
	v_pk_fma_f32 v[50:51], v[56:57], v[64:65], v[50:51] op_sel_hi:[1,0,1]
	v_pk_fma_f32 v[48:49], v[58:59], v[64:65], v[48:49] op_sel_hi:[1,0,1]
	v_pk_mul_f32 v[50:51], v[66:67], v[50:51] op_sel_hi:[0,1]
	v_pk_mul_f32 v[48:49], v[66:67], v[48:49] op_sel_hi:[0,1]
	v_cvt_pk_bf16_f32 v100, v50, v51
	v_cvt_pk_bf16_f32 v101, v48, v49
	s_waitcnt lgkmcnt(1)
	v_pk_mul_f32 v[48:49], v[70:71], v[52:53] op_sel_hi:[0,1]
	s_waitcnt lgkmcnt(0)
	v_pk_mul_f32 v[50:51], v[70:71], v[54:55] op_sel_hi:[0,1]
	v_pk_fma_f32 v[48:49], v[60:61], v[64:65], v[48:49] op_sel_hi:[1,0,1]
	v_pk_fma_f32 v[50:51], v[62:63], v[64:65], v[50:51] op_sel_hi:[1,0,1]
	v_pk_mul_f32 v[48:49], v[66:67], v[48:49] op_sel_hi:[0,1]
	v_pk_mul_f32 v[50:51], v[66:67], v[50:51] op_sel_hi:[0,1]
	v_cvt_pk_bf16_f32 v102, v48, v49
	v_cvt_pk_bf16_f32 v103, v50, v51
	ds_read2st64_b32 v[50:51], v67 offset0:16 offset1:17
	s_nop 1
	v_permlane32_swap_b32_e32 v100, v102
	v_permlane32_swap_b32_e32 v101, v103
	global_store_dwordx4 v[112:113], v[100:103], off offset:32
	ds_read2st64_b32 v[48:49], v67 offset0:18 offset1:19
	ds_read2st64_b32 v[52:53], v67 offset0:20 offset1:21
	ds_read2st64_b32 v[54:55], v67 offset0:22 offset1:23
	s_waitcnt lgkmcnt(3)
	v_pk_mul_f32 v[50:51], v[70:71], v[50:51] op_sel_hi:[0,1]
	s_waitcnt lgkmcnt(2)
	v_pk_mul_f32 v[48:49], v[70:71], v[48:49] op_sel_hi:[0,1]
	v_pk_fma_f32 v[32:33], v[32:33], v[64:65], v[50:51] op_sel_hi:[1,0,1]
	v_pk_fma_f32 v[34:35], v[34:35], v[64:65], v[48:49] op_sel_hi:[1,0,1]
	v_pk_mul_f32 v[32:33], v[66:67], v[32:33] op_sel_hi:[0,1]
	v_pk_mul_f32 v[34:35], v[66:67], v[34:35] op_sel_hi:[0,1]
	v_cvt_pk_bf16_f32 v104, v32, v33
	v_cvt_pk_bf16_f32 v105, v34, v35
	s_waitcnt lgkmcnt(1)
	v_pk_mul_f32 v[32:33], v[70:71], v[52:53] op_sel_hi:[0,1]
	s_waitcnt lgkmcnt(0)
	v_pk_mul_f32 v[34:35], v[70:71], v[54:55] op_sel_hi:[0,1]
	v_pk_fma_f32 v[32:33], v[36:37], v[64:65], v[32:33] op_sel_hi:[1,0,1]
	v_pk_fma_f32 v[34:35], v[38:39], v[64:65], v[34:35] op_sel_hi:[1,0,1]
	v_pk_mul_f32 v[32:33], v[66:67], v[32:33] op_sel_hi:[0,1]
	v_pk_mul_f32 v[34:35], v[66:67], v[34:35] op_sel_hi:[0,1]
	v_cvt_pk_bf16_f32 v106, v32, v33
	v_cvt_pk_bf16_f32 v107, v34, v35
	ds_read2st64_b32 v[34:35], v67 offset0:24 offset1:25
	s_nop 1
	v_permlane32_swap_b32_e32 v104, v106
	v_permlane32_swap_b32_e32 v105, v107
	global_store_dwordx4 v[112:113], v[104:107], off offset:64
	ds_read2st64_b32 v[32:33], v67 offset0:26 offset1:27
	ds_read2st64_b32 v[36:37], v67 offset0:28 offset1:29
	ds_read2st64_b32 v[38:39], v67 offset0:30 offset1:31
	s_waitcnt lgkmcnt(3)
; __device__ __forceinline__ unsigned pk2(float a, float b) { f32x2_t v = {a, b}; bf16x2v_t r = __builtin_convertvector(v, bf16x2v_t); return __builtin_bit_cast(unsigned, r); }
; __device__ __forceinline__ void attn_unit(LAS unsigned char* lds, const bf16_t* Qg, const bf16_t* Kg, const bf16_t* Vtg, bf16_t* Og, int bh, int qb, int tid_, int wave, int lane_) {
;     ...
; #pragma unroll
;         for (int dt = 0; dt < 4; ++dt)
; #pragma unroll
;             for (int g = 0; g < 4; ++g) {
;                 float v[4];
; #pragma unroll
;                 for (int e = 0; e < 4; ++e) v[e] = (o[dt][4 * g + e] * a0 + cs[(dt * 16 + 4 * g + e) * 64] * a1) * inv;
;                 u32x2 w; w.x = pk2(v[0], v[1]); w.y = pk2(v[2], v[3]);
;                 *(u32x2*)(op + 32 * dt + 8 * g) = w;
;             }
	v_pk_mul_f32 v[34:35], v[70:71], v[34:35] op_sel_hi:[0,1]
	s_waitcnt lgkmcnt(2)
	v_pk_mul_f32 v[32:33], v[70:71], v[32:33] op_sel_hi:[0,1]
	v_pk_fma_f32 v[34:35], v[40:41], v[64:65], v[34:35] op_sel_hi:[1,0,1]
	v_pk_fma_f32 v[32:33], v[42:43], v[64:65], v[32:33] op_sel_hi:[1,0,1]
	v_pk_mul_f32 v[34:35], v[66:67], v[34:35] op_sel_hi:[0,1]
	v_pk_mul_f32 v[32:33], v[66:67], v[32:33] op_sel_hi:[0,1]
	v_cvt_pk_bf16_f32 v108, v34, v35
	v_cvt_pk_bf16_f32 v109, v32, v33
	s_waitcnt lgkmcnt(1)
	v_pk_mul_f32 v[32:33], v[70:71], v[36:37] op_sel_hi:[0,1]
	s_waitcnt lgkmcnt(0)
	v_pk_mul_f32 v[34:35], v[70:71], v[38:39] op_sel_hi:[0,1]
	v_pk_fma_f32 v[32:33], v[44:45], v[64:65], v[32:33] op_sel_hi:[1,0,1]
	v_pk_fma_f32 v[34:35], v[46:47], v[64:65], v[34:35] op_sel_hi:[1,0,1]
	v_pk_mul_f32 v[32:33], v[66:67], v[32:33] op_sel_hi:[0,1]
	v_pk_mul_f32 v[34:35], v[66:67], v[34:35] op_sel_hi:[0,1]
	v_cvt_pk_bf16_f32 v110, v32, v33
	v_cvt_pk_bf16_f32 v111, v34, v35
	ds_read2st64_b32 v[34:35], v67 offset0:32 offset1:33
	s_nop 1
	v_permlane32_swap_b32_e32 v108, v110
	v_permlane32_swap_b32_e32 v109, v111
	global_store_dwordx4 v[112:113], v[108:111], off offset:96
	ds_read2st64_b32 v[32:33], v67 offset0:34 offset1:35
	ds_read2st64_b32 v[36:37], v67 offset0:36 offset1:37
	ds_read2st64_b32 v[38:39], v67 offset0:38 offset1:39
	s_waitcnt lgkmcnt(3)
	v_pk_mul_f32 v[34:35], v[70:71], v[34:35] op_sel_hi:[0,1]
	s_waitcnt lgkmcnt(2)
	v_pk_mul_f32 v[32:33], v[70:71], v[32:33] op_sel_hi:[0,1]
	v_pk_fma_f32 v[16:17], v[16:17], v[64:65], v[34:35] op_sel_hi:[1,0,1]
	v_pk_fma_f32 v[18:19], v[18:19], v[64:65], v[32:33] op_sel_hi:[1,0,1]
	v_pk_mul_f32 v[16:17], v[66:67], v[16:17] op_sel_hi:[0,1]
	v_pk_mul_f32 v[18:19], v[66:67], v[18:19] op_sel_hi:[0,1]
	v_cvt_pk_bf16_f32 v96, v16, v17
	v_cvt_pk_bf16_f32 v97, v18, v19
	s_waitcnt lgkmcnt(1)
	v_pk_mul_f32 v[16:17], v[70:71], v[36:37] op_sel_hi:[0,1]
	s_waitcnt lgkmcnt(0)
	v_pk_mul_f32 v[18:19], v[70:71], v[38:39] op_sel_hi:[0,1]
	v_pk_fma_f32 v[16:17], v[20:21], v[64:65], v[16:17] op_sel_hi:[1,0,1]
	v_pk_fma_f32 v[18:19], v[22:23], v[64:65], v[18:19] op_sel_hi:[1,0,1]
	v_pk_mul_f32 v[16:17], v[66:67], v[16:17] op_sel_hi:[0,1]
	v_pk_mul_f32 v[18:19], v[66:67], v[18:19] op_sel_hi:[0,1]
	v_cvt_pk_bf16_f32 v98, v16, v17
	v_cvt_pk_bf16_f32 v99, v18, v19
	ds_read2st64_b32 v[18:19], v67 offset0:40 offset1:41
	s_nop 1
	v_permlane32_swap_b32_e32 v96, v98
	v_permlane32_swap_b32_e32 v97, v99
	global_store_dwordx4 v[112:113], v[96:99], off offset:128
	ds_read2st64_b32 v[16:17], v67 offset0:42 offset1:43
	ds_read2st64_b32 v[20:21], v67 offset0:44 offset1:45
	ds_read2st64_b32 v[22:23], v67 offset0:46 offset1:47
	s_waitcnt lgkmcnt(3)
	v_pk_mul_f32 v[18:19], v[70:71], v[18:19] op_sel_hi:[0,1]
	s_waitcnt lgkmcnt(2)
	v_pk_mul_f32 v[16:17], v[70:71], v[16:17] op_sel_hi:[0,1]
	v_pk_fma_f32 v[18:19], v[24:25], v[64:65], v[18:19] op_sel_hi:[1,0,1]
	v_pk_fma_f32 v[16:17], v[26:27], v[64:65], v[16:17] op_sel_hi:[1,0,1]
	v_pk_mul_f32 v[18:19], v[66:67], v[18:19] op_sel_hi:[0,1]
	v_pk_mul_f32 v[16:17], v[66:67], v[16:17] op_sel_hi:[0,1]
	v_cvt_pk_bf16_f32 v100, v18, v19
	v_cvt_pk_bf16_f32 v101, v16, v17
	s_waitcnt lgkmcnt(1)
	v_pk_mul_f32 v[16:17], v[70:71], v[20:21] op_sel_hi:[0,1]
	s_waitcnt lgkmcnt(0)
	v_pk_mul_f32 v[18:19], v[70:71], v[22:23] op_sel_hi:[0,1]
	v_pk_fma_f32 v[16:17], v[28:29], v[64:65], v[16:17] op_sel_hi:[1,0,1]
	v_pk_fma_f32 v[18:19], v[30:31], v[64:65], v[18:19] op_sel_hi:[1,0,1]
	v_pk_mul_f32 v[16:17], v[66:67], v[16:17] op_sel_hi:[0,1]
	v_pk_mul_f32 v[18:19], v[66:67], v[18:19] op_sel_hi:[0,1]
	v_cvt_pk_bf16_f32 v102, v16, v17
	v_cvt_pk_bf16_f32 v103, v18, v19
	ds_read2st64_b32 v[18:19], v67 offset0:48 offset1:49
	s_nop 1
	v_permlane32_swap_b32_e32 v100, v102
	v_permlane32_swap_b32_e32 v101, v103
	global_store_dwordx4 v[112:113], v[100:103], off offset:160
	ds_read2st64_b32 v[16:17], v67 offset0:50 offset1:51
	ds_read2st64_b32 v[20:21], v67 offset0:52 offset1:53
	ds_read2st64_b32 v[22:23], v67 offset0:54 offset1:55
	s_waitcnt lgkmcnt(3)
	v_pk_mul_f32 v[18:19], v[70:71], v[18:19] op_sel_hi:[0,1]
	s_waitcnt lgkmcnt(2)
	v_pk_mul_f32 v[16:17], v[70:71], v[16:17] op_sel_hi:[0,1]
	v_pk_fma_f32 v[0:1], v[0:1], v[64:65], v[18:19] op_sel_hi:[1,0,1]
	v_pk_fma_f32 v[2:3], v[2:3], v[64:65], v[16:17] op_sel_hi:[1,0,1]
	v_pk_mul_f32 v[0:1], v[66:67], v[0:1] op_sel_hi:[0,1]
	v_pk_mul_f32 v[2:3], v[66:67], v[2:3] op_sel_hi:[0,1]
	v_cvt_pk_bf16_f32 v104, v0, v1
	v_cvt_pk_bf16_f32 v105, v2, v3
	s_waitcnt lgkmcnt(1)
	v_pk_mul_f32 v[0:1], v[70:71], v[20:21] op_sel_hi:[0,1]
	s_waitcnt lgkmcnt(0)
	v_pk_mul_f32 v[2:3], v[70:71], v[22:23] op_sel_hi:[0,1]
	v_pk_fma_f32 v[0:1], v[4:5], v[64:65], v[0:1] op_sel_hi:[1,0,1]
	v_pk_fma_f32 v[2:3], v[6:7], v[64:65], v[2:3] op_sel_hi:[1,0,1]
	v_pk_mul_f32 v[0:1], v[66:67], v[0:1] op_sel_hi:[0,1]
	v_pk_mul_f32 v[2:3], v[66:67], v[2:3] op_sel_hi:[0,1]
	v_cvt_pk_bf16_f32 v106, v0, v1
	v_cvt_pk_bf16_f32 v107, v2, v3
	ds_read2st64_b32 v[2:3], v67 offset0:56 offset1:57
	s_nop 1
	v_permlane32_swap_b32_e32 v104, v106
	v_permlane32_swap_b32_e32 v105, v107
	global_store_dwordx4 v[112:113], v[104:107], off offset:192
	ds_read2st64_b32 v[0:1], v67 offset0:58 offset1:59
	ds_read2st64_b32 v[4:5], v67 offset0:60 offset1:61
	ds_read2st64_b32 v[6:7], v67 offset0:62 offset1:63
	s_waitcnt lgkmcnt(3)
	v_pk_mul_f32 v[2:3], v[70:71], v[2:3] op_sel_hi:[0,1]
	s_waitcnt lgkmcnt(2)
	v_pk_mul_f32 v[0:1], v[70:71], v[0:1] op_sel_hi:[0,1]
	v_pk_fma_f32 v[2:3], v[8:9], v[64:65], v[2:3] op_sel_hi:[1,0,1]
	v_pk_fma_f32 v[0:1], v[10:11], v[64:65], v[0:1] op_sel_hi:[1,0,1]
	v_pk_mul_f32 v[2:3], v[66:67], v[2:3] op_sel_hi:[0,1]
	v_pk_mul_f32 v[0:1], v[66:67], v[0:1] op_sel_hi:[0,1]
	v_cvt_pk_bf16_f32 v108, v2, v3
	v_cvt_pk_bf16_f32 v109, v0, v1
	s_waitcnt lgkmcnt(1)
	v_pk_mul_f32 v[0:1], v[70:71], v[4:5] op_sel_hi:[0,1]
	s_waitcnt lgkmcnt(0)
	v_pk_mul_f32 v[2:3], v[70:71], v[6:7] op_sel_hi:[0,1]
	v_pk_fma_f32 v[0:1], v[12:13], v[64:65], v[0:1] op_sel_hi:[1,0,1]
	v_pk_fma_f32 v[2:3], v[14:15], v[64:65], v[2:3] op_sel_hi:[1,0,1]
	v_pk_mul_f32 v[0:1], v[66:67], v[0:1] op_sel_hi:[0,1]
	v_pk_mul_f32 v[2:3], v[66:67], v[2:3] op_sel_hi:[0,1]
	v_cvt_pk_bf16_f32 v110, v0, v1
	v_cvt_pk_bf16_f32 v111, v2, v3
	s_nop 1
	v_permlane32_swap_b32_e32 v108, v110
	v_permlane32_swap_b32_e32 v109, v111
	global_store_dwordx4 v[112:113], v[108:111], off offset:224

; __device__ __forceinline__ unsigned pk2(float a, float b) { f32x2_t v = {a, b}; bf16x2v_t r = __builtin_convertvector(v, bf16x2v_t); return __builtin_bit_cast(unsigned, r); }
; __device__ __forceinline__ void attn_unit(LAS unsigned char* lds, const bf16_t* Qg, const bf16_t* Kg, const bf16_t* Vtg, bf16_t* Og, int bh, int qb, int tid_, int wave, int lane_) {
;     ...
;     __syncthreads();
;     if (kh == 0) {
;         const float m1 = cs[64 * 64], l1 = cs[65 * 64];
;         const float mf = fmaxf(mrun, m1), a0 = __builtin_amdgcn_exp2f(mrun - mf), a1 = __builtin_amdgcn_exp2f(m1 - mf);
;         float lt = lrun * a0 + l1 * a1; lt += __shfl_xor(lt, 32);
;         const float inv = 1.f / lt;
;         bf16_t* op = Og + ((size_t)b * SEQ + 128 * qb + 32 * rg + r) * AW + h * VD + 4 * hi;
; #pragma unroll
;         for (int dt = 0; dt < 4; ++dt)
; #pragma unroll
;             for (int g = 0; g < 4; ++g) {
;                 float v[4];
; #pragma unroll
;                 for (int e = 0; e < 4; ++e) v[e] = (o[dt][4 * g + e] * a0 + cs[(dt * 16 + 4 * g + e) * 64] * a1) * inv;
;                 u32x2 w; w.x = pk2(v[0], v[1]); w.y = pk2(v[2], v[3]);
;                 *(u32x2*)(op + 32 * dt + 8 * g) = w;
;             }
;     }
.LBB0_497:
	s_and_b64 vcc, exec, s[6:7]
	s_waitcnt vmcnt(0) lgkmcnt(0)
	s_barrier
	s_cbranch_vccnz .LBB0_474
	ds_read2st64_b32 v[64:65], v67 offset0:64 offset1:65
	ds_read2st64_b32 v[72:73], v67 offset1:1
	v_max_f32_e32 v66, v198, v198
	v_xor_b32_e32 v70, 32, v197
	ds_read2st64_b32 v[74:75], v67 offset0:2 offset1:3
	ds_read2st64_b32 v[76:77], v67 offset0:4 offset1:5
	ds_read2st64_b32 v[78:79], v67 offset0:6 offset1:7
	s_waitcnt lgkmcnt(4)
	v_max_f32_e32 v68, v64, v64
	v_max_f32_e32 v66, v66, v68
	v_sub_f32_e32 v68, v198, v66
	v_sub_f32_e32 v66, v64, v66
	v_exp_f32_e32 v64, v68
	v_exp_f32_e32 v181, v66
	v_and_b32_e32 v66, 64, v197
	v_add_u32_e32 v66, 64, v66
	v_cmp_lt_i32_e32 vcc, v70, v66
	v_pk_mul_f32 v[68:69], v[180:181], v[64:65]
	v_lshlrev_b32_e32 v176, 3, v190
	v_cndmask_b32_e32 v66, v197, v70, vcc
	v_add_f32_e32 v65, v68, v69
	v_lshlrev_b32_e32 v66, 2, v66
	ds_bpermute_b32 v66, v66, v65
	s_waitcnt lgkmcnt(0)
	v_add_f32_e32 v65, v65, v66
	v_div_scale_f32 v66, s[0:1], v65, v65, 1.0
	v_rcp_f32_e32 v68, v66
	v_div_scale_f32 v69, vcc, 1.0, v65, 1.0
	s_lshl_b32 s0, s73, 11
	v_fma_f32 v70, -v66, v68, 1.0
	v_fmac_f32_e32 v68, v70, v68
	v_mul_f32_e32 v70, v69, v68
	v_fma_f32 v71, -v66, v70, v69
	v_fmac_f32_e32 v70, v71, v68
	v_fma_f32 v66, -v66, v70, v69
	s_and_b32 s0, s0, 0x2000
	v_div_fmas_f32 v66, v66, v68, v70
	s_add_u32 s0, s0, s50
	v_div_fixup_f32 v66, v66, v65, 1.0
	s_addc_u32 s1, 0, s51
	v_mov_b32_e32 v65, s97
	v_or3_b32 v69, s1, 0, 0
	v_or3_b32 v68, s0, v65, v191
	v_readlane_b32 s0, v255, 34
	v_mov_b32_e32 v70, v181
	v_lshlrev_b64 v[68:69], 10, v[68:69]
	v_readlane_b32 s1, v255, 35
	v_pk_mul_f32 v[72:73], v[70:71], v[72:73] op_sel_hi:[0,1]
	v_pk_fma_f32 v[48:49], v[48:49], v[64:65], v[72:73] op_sel_hi:[1,0,1]
	v_lshl_add_u64 v[68:69], s[0:1], 0, v[68:69]
	s_lshl_b32 s0, s73, 8
	v_pk_mul_f32 v[72:73], v[70:71], v[74:75] op_sel_hi:[0,1]
	s_and_b32 s48, s0, 0x300
	v_pk_fma_f32 v[50:51], v[50:51], v[64:65], v[72:73] op_sel_hi:[1,0,1]
	v_lshl_add_u64 v[68:69], v[68:69], 0, s[48:49]
	v_pk_mul_f32 v[48:49], v[48:49], v[66:67] op_sel_hi:[1,0]
	v_pk_mul_f32 v[50:51], v[66:67], v[50:51] op_sel_hi:[0,1]
	v_lshl_add_u64 v[68:69], v[68:69], 0, v[176:177]
	v_lshl_add_u64 v[112:113], v[68:69], 0, v[176:177]
	v_cvt_pk_bf16_f32 v96, v48, v49
	v_cvt_pk_bf16_f32 v97, v50, v51
	v_pk_mul_f32 v[48:49], v[70:71], v[76:77] op_sel_hi:[0,1]
	v_pk_mul_f32 v[50:51], v[70:71], v[78:79] op_sel_hi:[0,1]
	v_pk_fma_f32 v[48:49], v[52:53], v[64:65], v[48:49] op_sel_hi:[1,0,1]
	v_pk_fma_f32 v[50:51], v[54:55], v[64:65], v[50:51] op_sel_hi:[1,0,1]
	v_pk_mul_f32 v[48:49], v[66:67], v[48:49] op_sel_hi:[0,1]
	v_pk_mul_f32 v[50:51], v[66:67], v[50:51] op_sel_hi:[0,1]
	v_cvt_pk_bf16_f32 v98, v48, v49
	v_cvt_pk_bf16_f32 v99, v50, v51
	ds_read2st64_b32 v[50:51], v67 offset0:8 offset1:9
	s_nop 1
	v_permlane32_swap_b32_e32 v96, v98
	v_permlane32_swap_b32_e32 v97, v99
	global_store_dwordx4 v[112:113], v[96:99], off
	ds_read2st64_b32 v[48:49], v67 offset0:10 offset1:11
	ds_read2st64_b32 v[52:53], v67 offset0:12 offset1:13
	ds_read2st64_b32 v[54:55], v67 offset0:14 offset1:15
	s_waitcnt lgkmcnt(3)
	v_pk_mul_f32 v[50:51], v[70:71], v[50:51] op_sel_hi:[0,1]
	s_waitcnt lgkmcnt(2)
	v_pk_mul_f32 v[48:49], v[70:71], v[48:49] op_sel_hi:[0,1]
	v_pk_fma_f32 v[50:51], v[56:57], v[64:65], v[50:51] op_sel_hi:[1,0,1]
	v_pk_fma_f32 v[48:49], v[58:59], v[64:65], v[48:49] op_sel_hi:[1,0,1]
	v_pk_mul_f32 v[50:51], v[66:67], v[50:51] op_sel_hi:[0,1]
	v_pk_mul_f32 v[48:49], v[66:67], v[48:49] op_sel_hi:[0,1]
	v_cvt_pk_bf16_f32 v100, v50, v51
	v_cvt_pk_bf16_f32 v101, v48, v49
	s_waitcnt lgkmcnt(1)
	v_pk_mul_f32 v[48:49], v[70:71], v[52:53] op_sel_hi:[0,1]
	s_waitcnt lgkmcnt(0)
	v_pk_mul_f32 v[50:51], v[70:71], v[54:55] op_sel_hi:[0,1]
	v_pk_fma_f32 v[48:49], v[60:61], v[64:65], v[48:49] op_sel_hi:[1,0,1]
	v_pk_fma_f32 v[50:51], v[62:63], v[64:65], v[50:51] op_sel_hi:[1,0,1]
	v_pk_mul_f32 v[48:49], v[66:67], v[48:49] op_sel_hi:[0,1]
	v_pk_mul_f32 v[50:51], v[66:67], v[50:51] op_sel_hi:[0,1]
	v_cvt_pk_bf16_f32 v102, v48, v49
	v_cvt_pk_bf16_f32 v103, v50, v51
	ds_read2st64_b32 v[50:51], v67 offset0:16 offset1:17
	s_nop 1
	v_permlane32_swap_b32_e32 v100, v102
	v_permlane32_swap_b32_e32 v101, v103
	global_store_dwordx4 v[112:113], v[100:103], off offset:32
	ds_read2st64_b32 v[48:49], v67 offset0:18 offset1:19
	ds_read2st64_b32 v[52:53], v67 offset0:20 offset1:21
	ds_read2st64_b32 v[54:55], v67 offset0:22 offset1:23
	s_waitcnt lgkmcnt(3)
	v_pk_mul_f32 v[50:51], v[70:71], v[50:51] op_sel_hi:[0,1]
	s_waitcnt lgkmcnt(2)
	v_pk_mul_f32 v[48:49], v[70:71], v[48:49] op_sel_hi:[0,1]
	v_pk_fma_f32 v[32:33], v[32:33], v[64:65], v[50:51] op_sel_hi:[1,0,1]
	v_pk_fma_f32 v[34:35], v[34:35], v[64:65], v[48:49] op_sel_hi:[1,0,1]
	v_pk_mul_f32 v[32:33], v[66:67], v[32:33] op_sel_hi:[0,1]
	v_pk_mul_f32 v[34:35], v[66:67], v[34:35] op_sel_hi:[0,1]
	v_cvt_pk_bf16_f32 v104, v32, v33
	v_cvt_pk_bf16_f32 v105, v34, v35
	s_waitcnt lgkmcnt(1)
	v_pk_mul_f32 v[32:33], v[70:71], v[52:53] op_sel_hi:[0,1]
	s_waitcnt lgkmcnt(0)
	v_pk_mul_f32 v[34:35], v[70:71], v[54:55] op_sel_hi:[0,1]
	v_pk_fma_f32 v[32:33], v[36:37], v[64:65], v[32:33] op_sel_hi:[1,0,1]
	v_pk_fma_f32 v[34:35], v[38:39], v[64:65], v[34:35] op_sel_hi:[1,0,1]
	v_pk_mul_f32 v[32:33], v[66:67], v[32:33] op_sel_hi:[0,1]
	v_pk_mul_f32 v[34:35], v[66:67], v[34:35] op_sel_hi:[0,1]
	v_cvt_pk_bf16_f32 v106, v32, v33
	v_cvt_pk_bf16_f32 v107, v34, v35
	ds_read2st64_b32 v[34:35], v67 offset0:24 offset1:25
	s_nop 1
	v_permlane32_swap_b32_e32 v104, v106
	v_permlane32_swap_b32_e32 v105, v107
	global_store_dwordx4 v[112:113], v[104:107], off offset:64
	ds_read2st64_b32 v[32:33], v67 offset0:26 offset1:27
	ds_read2st64_b32 v[36:37], v67 offset0:28 offset1:29
	ds_read2st64_b32 v[38:39], v67 offset0:30 offset1:31
	s_waitcnt lgkmcnt(3)
; __device__ __forceinline__ unsigned pk2(float a, float b) { f32x2_t v = {a, b}; bf16x2v_t r = __builtin_convertvector(v, bf16x2v_t); return __builtin_bit_cast(unsigned, r); }
; __device__ __forceinline__ void attn_unit(LAS unsigned char* lds, const bf16_t* Qg, const bf16_t* Kg, const bf16_t* Vtg, bf16_t* Og, int bh, int qb, int tid_, int wave, int lane_) {
;     ...
; #pragma unroll
;         for (int dt = 0; dt < 4; ++dt)
; #pragma unroll
;             for (int g = 0; g < 4; ++g) {
;                 float v[4];
; #pragma unroll
;                 for (int e = 0; e < 4; ++e) v[e] = (o[dt][4 * g + e] * a0 + cs[(dt * 16 + 4 * g + e) * 64] * a1) * inv;
;                 u32x2 w; w.x = pk2(v[0], v[1]); w.y = pk2(v[2], v[3]);
;                 *(u32x2*)(op + 32 * dt + 8 * g) = w;
;             }
	v_pk_mul_f32 v[34:35], v[70:71], v[34:35] op_sel_hi:[0,1]
	s_waitcnt lgkmcnt(2)
	v_pk_mul_f32 v[32:33], v[70:71], v[32:33] op_sel_hi:[0,1]
	v_pk_fma_f32 v[34:35], v[40:41], v[64:65], v[34:35] op_sel_hi:[1,0,1]
	v_pk_fma_f32 v[32:33], v[42:43], v[64:65], v[32:33] op_sel_hi:[1,0,1]
	v_pk_mul_f32 v[34:35], v[66:67], v[34:35] op_sel_hi:[0,1]
	v_pk_mul_f32 v[32:33], v[66:67], v[32:33] op_sel_hi:[0,1]
	v_cvt_pk_bf16_f32 v108, v34, v35
	v_cvt_pk_bf16_f32 v109, v32, v33
	s_waitcnt lgkmcnt(1)
	v_pk_mul_f32 v[32:33], v[70:71], v[36:37] op_sel_hi:[0,1]
	s_waitcnt lgkmcnt(0)
	v_pk_mul_f32 v[34:35], v[70:71], v[38:39] op_sel_hi:[0,1]
	v_pk_fma_f32 v[32:33], v[44:45], v[64:65], v[32:33] op_sel_hi:[1,0,1]
	v_pk_fma_f32 v[34:35], v[46:47], v[64:65], v[34:35] op_sel_hi:[1,0,1]
	v_pk_mul_f32 v[32:33], v[66:67], v[32:33] op_sel_hi:[0,1]
	v_pk_mul_f32 v[34:35], v[66:67], v[34:35] op_sel_hi:[0,1]
	v_cvt_pk_bf16_f32 v110, v32, v33
	v_cvt_pk_bf16_f32 v111, v34, v35
	ds_read2st64_b32 v[34:35], v67 offset0:32 offset1:33
	s_nop 1
	v_permlane32_swap_b32_e32 v108, v110
	v_permlane32_swap_b32_e32 v109, v111
	global_store_dwordx4 v[112:113], v[108:111], off offset:96
	ds_read2st64_b32 v[32:33], v67 offset0:34 offset1:35
	ds_read2st64_b32 v[36:37], v67 offset0:36 offset1:37
	ds_read2st64_b32 v[38:39], v67 offset0:38 offset1:39
	s_waitcnt lgkmcnt(3)
	v_pk_mul_f32 v[34:35], v[70:71], v[34:35] op_sel_hi:[0,1]
	s_waitcnt lgkmcnt(2)
	v_pk_mul_f32 v[32:33], v[70:71], v[32:33] op_sel_hi:[0,1]
	v_pk_fma_f32 v[16:17], v[16:17], v[64:65], v[34:35] op_sel_hi:[1,0,1]
	v_pk_fma_f32 v[18:19], v[18:19], v[64:65], v[32:33] op_sel_hi:[1,0,1]
	v_pk_mul_f32 v[16:17], v[66:67], v[16:17] op_sel_hi:[0,1]
	v_pk_mul_f32 v[18:19], v[66:67], v[18:19] op_sel_hi:[0,1]
	v_cvt_pk_bf16_f32 v96, v16, v17
	v_cvt_pk_bf16_f32 v97, v18, v19
	s_waitcnt lgkmcnt(1)
	v_pk_mul_f32 v[16:17], v[70:71], v[36:37] op_sel_hi:[0,1]
	s_waitcnt lgkmcnt(0)
	v_pk_mul_f32 v[18:19], v[70:71], v[38:39] op_sel_hi:[0,1]
	v_pk_fma_f32 v[16:17], v[20:21], v[64:65], v[16:17] op_sel_hi:[1,0,1]
	v_pk_fma_f32 v[18:19], v[22:23], v[64:65], v[18:19] op_sel_hi:[1,0,1]
	v_pk_mul_f32 v[16:17], v[66:67], v[16:17] op_sel_hi:[0,1]
	v_pk_mul_f32 v[18:19], v[66:67], v[18:19] op_sel_hi:[0,1]
	v_cvt_pk_bf16_f32 v98, v16, v17
	v_cvt_pk_bf16_f32 v99, v18, v19
	ds_read2st64_b32 v[18:19], v67 offset0:40 offset1:41
	s_nop 1
	v_permlane32_swap_b32_e32 v96, v98
	v_permlane32_swap_b32_e32 v97, v99
	global_store_dwordx4 v[112:113], v[96:99], off offset:128
	ds_read2st64_b32 v[16:17], v67 offset0:42 offset1:43
	ds_read2st64_b32 v[20:21], v67 offset0:44 offset1:45
	ds_read2st64_b32 v[22:23], v67 offset0:46 offset1:47
	s_waitcnt lgkmcnt(3)
	v_pk_mul_f32 v[18:19], v[70:71], v[18:19] op_sel_hi:[0,1]
	s_waitcnt lgkmcnt(2)
	v_pk_mul_f32 v[16:17], v[70:71], v[16:17] op_sel_hi:[0,1]
	v_pk_fma_f32 v[18:19], v[24:25], v[64:65], v[18:19] op_sel_hi:[1,0,1]
	v_pk_fma_f32 v[16:17], v[26:27], v[64:65], v[16:17] op_sel_hi:[1,0,1]
	v_pk_mul_f32 v[18:19], v[66:67], v[18:19] op_sel_hi:[0,1]
	v_pk_mul_f32 v[16:17], v[66:67], v[16:17] op_sel_hi:[0,1]
	v_cvt_pk_bf16_f32 v100, v18, v19
	v_cvt_pk_bf16_f32 v101, v16, v17
	s_waitcnt lgkmcnt(1)
	v_pk_mul_f32 v[16:17], v[70:71], v[20:21] op_sel_hi:[0,1]
	s_waitcnt lgkmcnt(0)
	v_pk_mul_f32 v[18:19], v[70:71], v[22:23] op_sel_hi:[0,1]
	v_pk_fma_f32 v[16:17], v[28:29], v[64:65], v[16:17] op_sel_hi:[1,0,1]
	v_pk_fma_f32 v[18:19], v[30:31], v[64:65], v[18:19] op_sel_hi:[1,0,1]
	v_pk_mul_f32 v[16:17], v[66:67], v[16:17] op_sel_hi:[0,1]
	v_pk_mul_f32 v[18:19], v[66:67], v[18:19] op_sel_hi:[0,1]
	v_cvt_pk_bf16_f32 v102, v16, v17
	v_cvt_pk_bf16_f32 v103, v18, v19
	ds_read2st64_b32 v[18:19], v67 offset0:48 offset1:49
	s_nop 1
	v_permlane32_swap_b32_e32 v100, v102
	v_permlane32_swap_b32_e32 v101, v103
	global_store_dwordx4 v[112:113], v[100:103], off offset:160
	ds_read2st64_b32 v[16:17], v67 offset0:50 offset1:51
	ds_read2st64_b32 v[20:21], v67 offset0:52 offset1:53
	ds_read2st64_b32 v[22:23], v67 offset0:54 offset1:55
	s_waitcnt lgkmcnt(3)
	v_pk_mul_f32 v[18:19], v[70:71], v[18:19] op_sel_hi:[0,1]
	s_waitcnt lgkmcnt(2)
	v_pk_mul_f32 v[16:17], v[70:71], v[16:17] op_sel_hi:[0,1]
	v_pk_fma_f32 v[0:1], v[0:1], v[64:65], v[18:19] op_sel_hi:[1,0,1]
	v_pk_fma_f32 v[2:3], v[2:3], v[64:65], v[16:17] op_sel_hi:[1,0,1]
	v_pk_mul_f32 v[0:1], v[66:67], v[0:1] op_sel_hi:[0,1]
	v_pk_mul_f32 v[2:3], v[66:67], v[2:3] op_sel_hi:[0,1]
	v_cvt_pk_bf16_f32 v104, v0, v1
	v_cvt_pk_bf16_f32 v105, v2, v3
	s_waitcnt lgkmcnt(1)
	v_pk_mul_f32 v[0:1], v[70:71], v[20:21] op_sel_hi:[0,1]
	s_waitcnt lgkmcnt(0)
	v_pk_mul_f32 v[2:3], v[70:71], v[22:23] op_sel_hi:[0,1]
	v_pk_fma_f32 v[0:1], v[4:5], v[64:65], v[0:1] op_sel_hi:[1,0,1]
	v_pk_fma_f32 v[2:3], v[6:7], v[64:65], v[2:3] op_sel_hi:[1,0,1]
	v_pk_mul_f32 v[0:1], v[66:67], v[0:1] op_sel_hi:[0,1]
	v_pk_mul_f32 v[2:3], v[66:67], v[2:3] op_sel_hi:[0,1]
	v_cvt_pk_bf16_f32 v106, v0, v1
	v_cvt_pk_bf16_f32 v107, v2, v3
	ds_read2st64_b32 v[2:3], v67 offset0:56 offset1:57
	s_nop 1
	v_permlane32_swap_b32_e32 v104, v106
	v_permlane32_swap_b32_e32 v105, v107
	global_store_dwordx4 v[112:113], v[104:107], off offset:192
	ds_read2st64_b32 v[0:1], v67 offset0:58 offset1:59
	ds_read2st64_b32 v[4:5], v67 offset0:60 offset1:61
	ds_read2st64_b32 v[6:7], v67 offset0:62 offset1:63
	s_waitcnt lgkmcnt(3)
	v_pk_mul_f32 v[2:3], v[70:71], v[2:3] op_sel_hi:[0,1]
	s_waitcnt lgkmcnt(2)
	v_pk_mul_f32 v[0:1], v[70:71], v[0:1] op_sel_hi:[0,1]
	v_pk_fma_f32 v[2:3], v[8:9], v[64:65], v[2:3] op_sel_hi:[1,0,1]
	v_pk_fma_f32 v[0:1], v[10:11], v[64:65], v[0:1] op_sel_hi:[1,0,1]
	v_pk_mul_f32 v[2:3], v[66:67], v[2:3] op_sel_hi:[0,1]
	v_pk_mul_f32 v[0:1], v[66:67], v[0:1] op_sel_hi:[0,1]
	v_cvt_pk_bf16_f32 v108, v2, v3
	v_cvt_pk_bf16_f32 v109, v0, v1
	s_waitcnt lgkmcnt(1)
	v_pk_mul_f32 v[0:1], v[70:71], v[4:5] op_sel_hi:[0,1]
	s_waitcnt lgkmcnt(0)
	v_pk_mul_f32 v[2:3], v[70:71], v[6:7] op_sel_hi:[0,1]
	v_pk_fma_f32 v[0:1], v[12:13], v[64:65], v[0:1] op_sel_hi:[1,0,1]
	v_pk_fma_f32 v[2:3], v[14:15], v[64:65], v[2:3] op_sel_hi:[1,0,1]
	v_pk_mul_f32 v[0:1], v[66:67], v[0:1] op_sel_hi:[0,1]
	v_pk_mul_f32 v[2:3], v[66:67], v[2:3] op_sel_hi:[0,1]
	v_cvt_pk_bf16_f32 v110, v0, v1
	v_cvt_pk_bf16_f32 v111, v2, v3
	s_nop 1
	v_permlane32_swap_b32_e32 v108, v110
	v_permlane32_swap_b32_e32 v109, v111
	global_store_dwordx4 v[112:113], v[108:111], off offset:224
	s_branch .LBB0_474
